# chunk_state: all 12 raw tile loads requested at the top of the item
# baseline (speedup 1.0000x reference)
.LBB0_759:
	v_add_u32_e32 v0, s28, v66
	s_waitcnt vmcnt(6)
	v_min_i32_e32 v6, 0x1ff, v0
	v_mov_b32_e32 v82, v67
	v_and_b32_e32 v81, 7, v6
	v_cmp_gt_u32_e32 vcc, s29, v82
	v_lshlrev_b32_e32 v64, 2, v81
	v_ashrrev_i32_e32 v83, 3, v6
	v_cndmask_b32_e32 v5, v76, v77, vcc
	v_cndmask_b32_e32 v4, v78, v79, vcc
	v_lshl_add_u64 v[4:5], v[4:5], 0, v[64:65]
	v_lshrrev_b32_e32 v114, 4, v82
	v_and_b32_e32 v115, 15, v82
	v_lshlrev_b32_e32 v115, 4, v115
	v_lshl_add_u32 v116, v83, 8, v115
	v_lshl_add_u32 v117, v81, 6, v114
	v_lshl_add_u32 v117, v117, 14, v116
	v_lshrrev_b32_e32 v118, 2, v81
	v_lshl_add_u32 v118, v118, 7, v114
	v_lshl_add_u32 v118, v118, 14, v116
	global_load_dwordx4 v[120:123], v117, s[16:17]
	v_add_u32_e32 v117, 0x40000, v117
	global_load_dwordx4 v[124:127], v117, s[16:17]
	v_add_u32_e32 v117, 0x40000, v117
	global_load_dwordx4 v[128:131], v117, s[16:17]
	v_add_u32_e32 v117, 0x40000, v117
	global_load_dwordx4 v[132:135], v117, s[16:17]
	global_load_dwordx4 v[136:139], v118, s[18:19]
	v_add_u32_e32 v118, 0x40000, v118
	global_load_dwordx4 v[140:143], v118, s[18:19]
	v_add_u32_e32 v118, 0x40000, v118
	global_load_dwordx4 v[144:147], v118, s[18:19]
	v_add_u32_e32 v118, 0x40000, v118
	global_load_dwordx4 v[148:151], v118, s[18:19]
	v_add_u32_e32 v118, 0x40000, v118
	global_load_dwordx4 v[152:155], v118, s[18:19]
	v_add_u32_e32 v118, 0x40000, v118
	global_load_dwordx4 v[156:159], v118, s[18:19]
	v_add_u32_e32 v118, 0x40000, v118
	global_load_dwordx4 v[160:163], v118, s[18:19]
	v_add_u32_e32 v118, 0x40000, v118
	global_load_dwordx4 v[164:167], v118, s[18:19]
	global_load_dword v10, v[4:5], off
	v_ashrrev_i32_e32 v2, 7, v82
	v_lshlrev_b32_e32 v0, 7, v83
	v_ashrrev_i32_e32 v3, 31, v2
	v_lshlrev_b64 v[4:5], 13, v[2:3]
	v_ashrrev_i32_e32 v1, 31, v0
	v_and_b32_e32 v7, 0x7f, v82
	v_lshl_add_u64 v[4:5], v[4:5], 0, v[0:1]
	v_or_b32_e32 v4, v4, v7
	v_lshlrev_b64 v[4:5], 3, v[4:5]
	v_or_b32_e32 v4, v4, v81
	s_waitcnt vmcnt(6)
	v_lshl_add_u64 v[8:9], v[4:5], 2, s[6:7]
	global_load_dword v9, v[8:9], off
	v_lshlrev_b32_e32 v3, 2, v82
	v_cmp_lt_u32_e32 vcc, s15, v82
	s_waitcnt vmcnt(6)
	v_add_u32_e32 v13, v68, v3
	s_waitcnt vmcnt(1)
	v_mul_f32_e32 v8, 0x3fb8aa3b, v10
	v_fma_f32 v11, v10, s30, -v8
	v_rndne_f32_e32 v12, v8
	v_fmac_f32_e32 v11, 0x32a5705f, v10
	v_sub_f32_e32 v8, v8, v12
	v_add_f32_e32 v8, v8, v11
	v_cvt_i32_f32_e32 v12, v12
	v_exp_f32_e32 v11, v8
	v_cmp_ngt_f32_e64 s[4:5], s31, v10
	v_add_u32_e32 v8, v71, v3
	v_ldexp_f32 v11, v11, v12
	v_cndmask_b32_e64 v11, 0, v11, s[4:5]
	v_cmp_nlt_f32_e64 s[4:5], s33, v10
	s_waitcnt vmcnt(0)
	ds_write_b32 v8, v9
	v_cndmask_b32_e64 v10, v80, v11, s[4:5]
	v_mul_f32_e64 v9, v9, -v10
	ds_write_b32 v13, v9
	s_waitcnt lgkmcnt(0)
	s_barrier
	s_and_saveexec_b64 s[4:5], vcc
	s_xor_b64 s[4:5], exec, s[4:5]
	s_cbranch_execz .LBB0_769
	v_add_u32_e32 v10, 3, v7
	v_cmp_gt_u32_e32 vcc, s36, v7
	v_mov_b32_e32 v9, 0
	s_and_saveexec_b64 s[22:23], vcc
	s_cbranch_execz .LBB0_764
	v_and_b32_e32 v9, 0xfffffe00, v3
	v_lshrrev_b32_e32 v11, 2, v10
	v_add_u32_e32 v12, v72, v9
	v_mov_b32_e32 v9, 0
	s_mov_b32 s26, 32
	s_mov_b64 s[24:25], 0

.LBB0_787:
	s_or_b64 exec, exec, s[4:5]
	v_lshlrev_b32_e32 v2, 3, v82
	v_lshlrev_b32_e32 v7, 6, v81
	v_ashrrev_i32_e32 v42, 4, v82
	v_and_b32_e32 v6, 0x78, v2
	v_add_u32_e32 v2, v42, v7
	v_ashrrev_i32_e32 v3, 31, v2
	v_lshlrev_b64 v[2:3], 14, v[2:3]
	v_lshl_add_u64 v[2:3], s[16:17], 0, v[2:3]
	v_lshlrev_b64 v[4:5], 1, v[0:1]
	v_lshlrev_b32_e32 v64, 1, v6
	v_lshl_add_u64 v[0:1], v[2:3], 0, v[4:5]
	v_lshl_add_u64 v[0:1], v[0:1], 0, v[64:65]
	s_waitcnt lgkmcnt(0)
	s_barrier
	v_mov_b32_e32 v10, v120
	v_mov_b32_e32 v11, v121
	v_mov_b32_e32 v12, v122
	v_mov_b32_e32 v13, v123
	v_add_u32_e32 v0, 0x100, v82
	v_ashrrev_i32_e32 v43, 4, v0
	v_add_u32_e32 v0, v43, v7
	v_ashrrev_i32_e32 v1, 31, v0
	v_lshlrev_b64 v[0:1], 14, v[0:1]
	v_lshl_add_u64 v[0:1], s[16:17], 0, v[0:1]
	v_lshl_add_u64 v[0:1], v[0:1], 0, v[4:5]
	v_lshl_add_u64 v[0:1], v[0:1], 0, v[64:65]
	v_mov_b32_e32 v14, v124
	v_mov_b32_e32 v15, v125
	v_mov_b32_e32 v16, v126
	v_mov_b32_e32 v17, v127
	v_add_u32_e32 v0, 0x200, v82
	v_ashrrev_i32_e32 v86, 4, v0
	v_lshl_add_u32 v87, v6, 2, v70
	v_add_u32_e32 v0, v86, v7
	ds_read_b128 v[18:21], v87
	ds_read_b128 v[22:25], v87 offset:16
	ds_read_b128 v[26:29], v87 offset:512
	ds_read_b128 v[30:33], v87 offset:528
	v_ashrrev_i32_e32 v1, 31, v0
	v_lshlrev_b64 v[0:1], 14, v[0:1]
	v_lshl_add_u64 v[0:1], s[16:17], 0, v[0:1]
	v_add_u32_e32 v6, v96, v64
	v_lshl_add_u64 v[0:1], v[0:1], 0, v[4:5]
	v_mad_u64_u32 v[8:9], s[4:5], v42, s37, v[6:7]
	v_lshl_add_u64 v[0:1], v[0:1], 0, v[64:65]
	v_mov_b32_e32 v0, v128
	v_mov_b32_e32 v1, v129
	v_mov_b32_e32 v2, v130
	v_mov_b32_e32 v3, v131
	v_add_u32_e32 v9, 0x300, v82
	v_ashrrev_i32_e32 v9, 4, v9
	v_add_u32_e32 v44, 0x700, v82
	v_ashrrev_i32_e32 v90, 4, v44
	v_and_b32_e32 v84, 15, v82
	v_bfe_u32 v85, v82, 4, 2
	v_lshlrev_b32_e32 v34, 16, v10
	v_and_b32_e32 v35, 0xffff0000, v10
	v_lshlrev_b32_e32 v10, 16, v11
	v_and_b32_e32 v11, 0xffff0000, v11
	v_lshlrev_b32_e32 v36, 16, v12
	v_and_b32_e32 v37, 0xffff0000, v12
	v_lshlrev_b32_e32 v12, 16, v13
	v_and_b32_e32 v13, 0xffff0000, v13
	s_waitcnt lgkmcnt(3)
	v_pk_mul_f32 v[18:19], v[18:19], v[34:35]
	v_pk_mul_f32 v[20:21], v[20:21], v[10:11]
	s_waitcnt lgkmcnt(2)
	v_pk_mul_f32 v[22:23], v[22:23], v[36:37]
	v_pk_mul_f32 v[24:25], v[24:25], v[12:13]
	s_waitcnt lgkmcnt(1)
	v_pk_mul_f32 v[26:27], v[26:27], v[34:35]
	v_pk_mul_f32 v[28:29], v[28:29], v[10:11]
	s_waitcnt lgkmcnt(0)
	v_pk_mul_f32 v[30:31], v[30:31], v[36:37]
	v_pk_mul_f32 v[32:33], v[32:33], v[12:13]
	v_cvt_pk_bf16_f32 v10, v18, v19
	v_cvt_pk_bf16_f32 v11, v20, v21
	v_cvt_pk_bf16_f32 v12, v22, v23
	v_cvt_pk_bf16_f32 v13, v24, v25
	v_cvt_pk_bf16_f32 v18, v26, v27
	v_cvt_pk_bf16_f32 v19, v28, v29
	v_cvt_pk_bf16_f32 v20, v30, v31
	v_cvt_pk_bf16_f32 v21, v32, v33
	ds_write_b128 v8, v[10:13]
	ds_write_b128 v8, v[18:21] offset:17408
	v_lshlrev_b32_e32 v34, 16, v14
	v_and_b32_e32 v35, 0xffff0000, v14
	v_lshlrev_b32_e32 v36, 16, v15
	v_and_b32_e32 v37, 0xffff0000, v15
	v_lshlrev_b32_e32 v38, 16, v16
	v_and_b32_e32 v39, 0xffff0000, v16
	v_lshlrev_b32_e32 v40, 16, v17
	ds_read_b128 v[10:13], v87
	ds_read_b128 v[18:21], v87 offset:512
	v_and_b32_e32 v41, 0xffff0000, v17
	ds_read_b128 v[14:17], v87 offset:16
	ds_read_b128 v[22:25], v87 offset:528
	s_waitcnt lgkmcnt(3)
	v_pk_mul_f32 v[10:11], v[10:11], v[34:35]
	v_pk_mul_f32 v[26:27], v[12:13], v[36:37]
	s_waitcnt lgkmcnt(1)
	v_pk_mul_f32 v[14:15], v[14:15], v[38:39]
	v_pk_mul_f32 v[28:29], v[16:17], v[40:41]
	v_pk_mul_f32 v[18:19], v[18:19], v[34:35]
	v_pk_mul_f32 v[20:21], v[20:21], v[36:37]
	s_waitcnt lgkmcnt(0)
	v_pk_mul_f32 v[22:23], v[22:23], v[38:39]
	v_pk_mul_f32 v[24:25], v[24:25], v[40:41]
	v_cvt_pk_bf16_f32 v12, v10, v11
	v_cvt_pk_bf16_f32 v13, v26, v27
	v_cvt_pk_bf16_f32 v14, v14, v15
	v_cvt_pk_bf16_f32 v15, v28, v29
	v_mad_u64_u32 v[10:11], s[4:5], v43, s37, v[6:7]
	v_cvt_pk_bf16_f32 v16, v18, v19
	v_cvt_pk_bf16_f32 v17, v20, v21
	v_cvt_pk_bf16_f32 v18, v22, v23
	v_cvt_pk_bf16_f32 v19, v24, v25
	ds_write_b128 v10, v[12:15]
	ds_write_b128 v10, v[16:19] offset:17408
	v_add_u32_e32 v12, v9, v7
	v_lshlrev_b32_e32 v7, 5, v81
	v_and_b32_e32 v7, 0x80, v7
	v_add_u32_e32 v14, v42, v7
	v_ashrrev_i32_e32 v13, 31, v12
	v_ashrrev_i32_e32 v15, 31, v14
	v_lshlrev_b64 v[12:13], 14, v[12:13]
	v_lshlrev_b64 v[14:15], 14, v[14:15]
	v_lshl_add_u64 v[12:13], s[16:17], 0, v[12:13]
	v_lshl_add_u64 v[14:15], s[18:19], 0, v[14:15]
	v_lshl_add_u64 v[12:13], v[12:13], 0, v[4:5]
	v_lshl_add_u64 v[14:15], v[14:15], 0, v[4:5]
	v_lshl_add_u64 v[12:13], v[12:13], 0, v[64:65]
	v_lshl_add_u64 v[16:17], v[14:15], 0, v[64:65]
	v_mov_b32_e32 v12, v132
	v_mov_b32_e32 v13, v133
	v_mov_b32_e32 v14, v134
	v_mov_b32_e32 v15, v135
	s_nop 0
	v_mov_b32_e32 v16, v136
	v_mov_b32_e32 v17, v137
	v_mov_b32_e32 v18, v138
	v_mov_b32_e32 v19, v139
	v_add_u32_e32 v11, 0x400, v82
	v_add_u32_e32 v20, v43, v7
	v_add_u32_e32 v22, v86, v7
	v_ashrrev_i32_e32 v11, 4, v11
	v_ashrrev_i32_e32 v21, 31, v20
	v_ashrrev_i32_e32 v23, 31, v22
	v_add_u32_e32 v28, v9, v7
	v_add_u32_e32 v30, v11, v7
	v_add_u32_e32 v36, 0x500, v82
	v_add_u32_e32 v38, 0x600, v82
	v_lshlrev_b64 v[20:21], 14, v[20:21]
	v_lshlrev_b64 v[22:23], 14, v[22:23]
	v_ashrrev_i32_e32 v29, 31, v28
	v_ashrrev_i32_e32 v31, 31, v30
	v_ashrrev_i32_e32 v88, 4, v36
	v_ashrrev_i32_e32 v89, 4, v38
	v_lshl_add_u64 v[20:21], s[18:19], 0, v[20:21]
	v_lshl_add_u64 v[22:23], s[18:19], 0, v[22:23]
	v_lshlrev_b64 v[28:29], 14, v[28:29]
	v_lshlrev_b64 v[30:31], 14, v[30:31]
	v_add_u32_e32 v36, v88, v7
	v_add_u32_e32 v38, v89, v7
	v_lshl_add_u64 v[20:21], v[20:21], 0, v[4:5]
	v_lshl_add_u64 v[22:23], v[22:23], 0, v[4:5]
	v_lshl_add_u64 v[28:29], s[18:19], 0, v[28:29]
	v_lshl_add_u64 v[30:31], s[18:19], 0, v[30:31]
	v_ashrrev_i32_e32 v37, 31, v36
	v_ashrrev_i32_e32 v39, 31, v38
	v_add_u32_e32 v44, v90, v7
	v_lshl_add_u64 v[20:21], v[20:21], 0, v[64:65]
	v_lshl_add_u64 v[24:25], v[22:23], 0, v[64:65]
	v_lshl_add_u64 v[28:29], v[28:29], 0, v[4:5]
	v_lshl_add_u64 v[30:31], v[30:31], 0, v[4:5]
	v_lshlrev_b64 v[36:37], 14, v[36:37]
	v_lshlrev_b64 v[38:39], 14, v[38:39]
	v_ashrrev_i32_e32 v45, 31, v44
	v_mov_b32_e32 v20, v140
	v_mov_b32_e32 v21, v141
	v_mov_b32_e32 v22, v142
	v_mov_b32_e32 v23, v143
	s_nop 0
	v_mov_b32_e32 v24, v144
	v_mov_b32_e32 v25, v145
	v_mov_b32_e32 v26, v146
	v_mov_b32_e32 v27, v147
	v_lshl_add_u64 v[28:29], v[28:29], 0, v[64:65]
	v_lshl_add_u64 v[32:33], v[30:31], 0, v[64:65]
	v_lshl_add_u64 v[36:37], s[18:19], 0, v[36:37]
	v_lshl_add_u64 v[38:39], s[18:19], 0, v[38:39]
	v_lshlrev_b64 v[44:45], 14, v[44:45]
	v_mov_b32_e32 v28, v148
	v_mov_b32_e32 v29, v149
	v_mov_b32_e32 v30, v150
	v_mov_b32_e32 v31, v151
	s_nop 0
	v_mov_b32_e32 v32, v152
	v_mov_b32_e32 v33, v153
	v_mov_b32_e32 v34, v154
	v_mov_b32_e32 v35, v155
	v_lshl_add_u64 v[36:37], v[36:37], 0, v[4:5]
	v_lshl_add_u64 v[38:39], v[38:39], 0, v[4:5]
	v_lshl_add_u64 v[44:45], s[18:19], 0, v[44:45]
	v_lshl_add_u64 v[36:37], v[36:37], 0, v[64:65]
	v_lshl_add_u64 v[40:41], v[38:39], 0, v[64:65]
	v_lshl_add_u64 v[4:5], v[44:45], 0, v[4:5]
	v_mov_b32_e32 v36, v156
	v_mov_b32_e32 v37, v157
	v_mov_b32_e32 v38, v158
	v_mov_b32_e32 v39, v159
	s_nop 0
	v_mov_b32_e32 v40, v160
	v_mov_b32_e32 v41, v161
	v_mov_b32_e32 v42, v162
	v_mov_b32_e32 v43, v163
	v_lshl_add_u64 v[4:5], v[4:5], 0, v[64:65]
	v_mov_b32_e32 v44, v164
	v_mov_b32_e32 v45, v165
	v_mov_b32_e32 v46, v166
	v_mov_b32_e32 v47, v167
	ds_read_b128 v[48:51], v87
	ds_read_b128 v[52:55], v87 offset:512
	ds_read_b128 v[56:59], v87 offset:16
	v_lshlrev_b32_e32 v4, 16, v0
	v_and_b32_e32 v5, 0xffff0000, v0
	ds_read_b128 v[60:63], v87 offset:528
	s_waitcnt lgkmcnt(3)
	v_pk_mul_f32 v[48:49], v[48:49], v[4:5]
	s_waitcnt lgkmcnt(2)
	v_pk_mul_f32 v[4:5], v[52:53], v[4:5]
	v_cvt_pk_bf16_f32 v0, v48, v49
	v_cvt_pk_bf16_f32 v48, v4, v5
	v_lshlrev_b32_e32 v4, 16, v1
	v_and_b32_e32 v5, 0xffff0000, v1
	v_pk_mul_f32 v[50:51], v[50:51], v[4:5]
	v_pk_mul_f32 v[4:5], v[54:55], v[4:5]
	v_cvt_pk_bf16_f32 v1, v50, v51
	v_cvt_pk_bf16_f32 v49, v4, v5
	v_lshlrev_b32_e32 v4, 16, v2
	v_and_b32_e32 v5, 0xffff0000, v2
	s_waitcnt lgkmcnt(1)
	v_pk_mul_f32 v[50:51], v[56:57], v[4:5]
	s_waitcnt lgkmcnt(0)
	v_pk_mul_f32 v[4:5], v[60:61], v[4:5]
	v_cvt_pk_bf16_f32 v2, v50, v51
	v_cvt_pk_bf16_f32 v50, v4, v5
	v_lshlrev_b32_e32 v4, 16, v3
	v_and_b32_e32 v5, 0xffff0000, v3
	v_pk_mul_f32 v[52:53], v[58:59], v[4:5]
	v_pk_mul_f32 v[4:5], v[62:63], v[4:5]
	v_cvt_pk_bf16_f32 v3, v52, v53
	v_cvt_pk_bf16_f32 v51, v4, v5
	v_mad_u64_u32 v[4:5], s[4:5], v86, s37, v[6:7]
	ds_write_b128 v4, v[0:3]
	ds_write_b128 v4, v[48:51] offset:17408
	ds_read_b128 v[0:3], v87
	ds_read_b128 v[48:51], v87 offset:512
	ds_read_b128 v[52:55], v87 offset:16
	v_lshlrev_b32_e32 v60, 16, v12
	v_and_b32_e32 v61, 0xffff0000, v12
	ds_read_b128 v[56:59], v87 offset:528
	s_waitcnt lgkmcnt(2)
	v_pk_mul_f32 v[48:49], v[48:49], v[60:61]
	v_pk_mul_f32 v[0:1], v[0:1], v[60:61]
	v_cvt_pk_bf16_f32 v12, v48, v49
	v_lshlrev_b32_e32 v48, 16, v13
	v_and_b32_e32 v49, 0xffff0000, v13
	v_pk_mul_f32 v[2:3], v[2:3], v[48:49]
	v_cvt_pk_bf16_f32 v0, v0, v1
	v_cvt_pk_bf16_f32 v1, v2, v3
	v_pk_mul_f32 v[2:3], v[50:51], v[48:49]
	v_lshlrev_b32_e32 v48, 16, v14
	v_and_b32_e32 v49, 0xffff0000, v14
	v_cvt_pk_bf16_f32 v13, v2, v3
	s_waitcnt lgkmcnt(1)
	v_pk_mul_f32 v[2:3], v[52:53], v[48:49]
	s_waitcnt lgkmcnt(0)
	v_pk_mul_f32 v[48:49], v[56:57], v[48:49]
	v_cvt_pk_bf16_f32 v2, v2, v3
	v_cvt_pk_bf16_f32 v14, v48, v49
	v_lshlrev_b32_e32 v48, 16, v15
	v_and_b32_e32 v49, 0xffff0000, v15
	v_pk_mul_f32 v[50:51], v[54:55], v[48:49]
	v_pk_mul_f32 v[48:49], v[58:59], v[48:49]
	v_cvt_pk_bf16_f32 v3, v50, v51
	v_cvt_pk_bf16_f32 v15, v48, v49
	v_mad_u64_u32 v[48:49], s[4:5], v9, s37, v[6:7]
	ds_write_b128 v48, v[0:3]
	ds_write_b128 v48, v[12:15] offset:17408
	ds_write_b128 v8, v[16:19] offset:34816
	ds_write_b128 v10, v[20:23] offset:34816
	ds_write_b128 v4, v[24:27] offset:34816
	ds_write_b128 v48, v[28:31] offset:34816
	v_mad_u64_u32 v[0:1], s[4:5], v11, s37, v[6:7]
	ds_write_b128 v0, v[32:35] offset:34816
	v_mad_u64_u32 v[0:1], s[4:5], v88, s37, v[6:7]
	v_lshlrev_b32_e32 v2, 4, v85
	ds_write_b128 v0, v[36:39] offset:34816
	v_mad_u64_u32 v[0:1], s[4:5], v89, s37, v[6:7]
	ds_write_b128 v0, v[40:43] offset:34816
	v_mad_u64_u32 v[0:1], s[4:5], v90, s37, v[6:7]
	ds_write_b128 v0, v[44:47] offset:34816
	v_ashrrev_i32_e32 v0, 1, v82
	v_and_b32_e32 v64, 0xffffffc0, v0
	v_mad_u64_u32 v[0:1], s[4:5], v64, s37, v[96:97]
	v_mul_u32_u24_e32 v1, 0x110, v84
	v_add3_u32 v86, v0, v1, v2
	v_and_b32_e32 v0, 0x4f, v82
	v_mul_u32_u24_e32 v0, 0x110, v0
	v_add3_u32 v87, v0, v2, v75
	v_mov_b32_e32 v0, 0
	s_mov_b32 s4, 0
	v_mov_b32_e32 v1, v0
	v_mov_b32_e32 v2, v0
	v_mov_b32_e32 v3, v0
	v_mov_b32_e32 v4, v0
	v_mov_b32_e32 v5, v0
	v_mov_b32_e32 v6, v0
	v_mov_b32_e32 v7, v0
	v_mov_b32_e32 v8, v0
	v_mov_b32_e32 v9, v0
	v_mov_b32_e32 v10, v0
	v_mov_b32_e32 v11, v0
	v_mov_b32_e32 v12, v0
	v_mov_b32_e32 v13, v0
	v_mov_b32_e32 v14, v0
	v_mov_b32_e32 v15, v0
	v_mov_b32_e32 v16, v0
	v_mov_b32_e32 v17, v0
	v_mov_b32_e32 v18, v0
	v_mov_b32_e32 v19, v0
	v_mov_b32_e32 v20, v0
	v_mov_b32_e32 v21, v0
	v_mov_b32_e32 v22, v0
	v_mov_b32_e32 v23, v0
	v_mov_b32_e32 v24, v0
	v_mov_b32_e32 v25, v0
	v_mov_b32_e32 v26, v0
	v_mov_b32_e32 v27, v0
	v_mov_b32_e32 v28, v0
	v_mov_b32_e32 v29, v0
	v_mov_b32_e32 v30, v0
	v_mov_b32_e32 v31, v0
	v_mov_b32_e32 v32, v0
	v_mov_b32_e32 v33, v0
	v_mov_b32_e32 v34, v0
	v_mov_b32_e32 v35, v0
	v_mov_b32_e32 v36, v0
	v_mov_b32_e32 v37, v0
	v_mov_b32_e32 v38, v0
	v_mov_b32_e32 v39, v0
	v_mov_b32_e32 v40, v0
	v_mov_b32_e32 v41, v0
	v_mov_b32_e32 v42, v0
	v_mov_b32_e32 v43, v0
	v_mov_b32_e32 v44, v0
	v_mov_b32_e32 v45, v0
	v_mov_b32_e32 v46, v0
	v_mov_b32_e32 v47, v0
	v_mov_b32_e32 v48, v0
	v_mov_b32_e32 v49, v0
	v_mov_b32_e32 v50, v0
	v_mov_b32_e32 v51, v0
	v_mov_b32_e32 v52, v0
	v_mov_b32_e32 v53, v0
	v_mov_b32_e32 v54, v0
	v_mov_b32_e32 v55, v0
	v_mov_b32_e32 v56, v0
	v_mov_b32_e32 v57, v0
	v_mov_b32_e32 v58, v0
	v_mov_b32_e32 v59, v0
	v_mov_b32_e32 v60, v0
	v_mov_b32_e32 v61, v0
	v_mov_b32_e32 v62, v0
	v_mov_b32_e32 v63, v0
	s_waitcnt lgkmcnt(0)
	s_barrier
